# scan phases: waves 4-7 raised exclusively (others reset to 0 at scan entry); GEMM: flips deleted + waves 0-3 raised
# baseline (speedup 1.0000x reference)
; __device__ __forceinline__ void ssd_phase(const Args& A, unsigned char* smem, const bool dry) {
;     ...
;     for (int u = blockIdx.x; u < 256; u += gridDim.x) {
;         const int b = u >> 4, h = u & 15, g = h >> 2;
;         __syncthreads();
.LBB0_415:
	s_setprio 0
	v_readfirstlane_b32 s98, v152
	s_nop 3
	s_cmp_ge_u32 s98, 0x100
	s_cbranch_scc0 .Lsp0_skip
	s_setprio 1
